# NA attention tasks in XCD-local order: the 8 query blocks of one (batch, head) run on one XCD and share K/V through its L2
# speedup vs baseline: 1.0105x; 1.0105x over previous
; __device__ __forceinline__ int otid() { int t = threadIdx.x; asm volatile("" : "+v"(t)); return t; }
; __device__ __forceinline__ void na_task(const Params& p, int task, char* shm) {
;   const int qb = task & 7, h = (task >> 3) & 7, b = task >> 6;
;   const bf16_t* P = (const bf16_t*)(p.ws + OFF_P); bf16_t* MIX = (bf16_t*)(p.ws + OFF_MIX);
;   __syncthreads();
;   { float* tb = (float*)(shm + 2 * att::SHM_V + 2 * (64 * 128 * 2) + att::NW * 256) + 64;
;     for (int i = otid(); i < 15 * 31; i += 512) tb[i] = p.in[12][h * 465 + i] * 11.313708498984761f; }
.LBB0_405:
	s_andn2_b64 vcc, exec, s[4:5]
	s_cbranch_vccnz .LBB0_322
	s_bfe_u32 s99, s89, 0x30003
	s_bfe_u32 s100, s89, 0x20006
	s_lshl_b32 s100, s100, 3
	s_or_b32 s99, s99, s100
	s_and_b32 s100, s89, 7
	s_lshl_b32 s100, s100, 5
	s_or_b32 s99, s99, s100
	s_and_b32 s100, s89, 0x100
	s_or_b32 s99, s99, s100
	v_mov_b32_e32 v0, v170
	s_movk_i32 s0, 0x1d1
	s_bfe_u32 s96, s99, 0x30003
	s_waitcnt lgkmcnt(0)
	s_barrier
	s_nop 0
	v_cmp_gt_i32_e32 vcc, s0, v0
	s_and_saveexec_b64 s[4:5], vcc
	s_cbranch_execz .LBB0_419
	v_max_i32_e32 v1, 0xffffffd1, v0
	v_sub_u32_e32 v1, v1, v0
	v_add_u32_e32 v1, 0x1ff, v1
	s_movk_i32 s0, 0x1ff
	v_cmp_lt_u32_e32 vcc, s0, v1
	s_mov_b64 s[8:9], -1
	s_and_saveexec_b64 s[6:7], vcc
	s_cbranch_execz .LBB0_416
	v_lshrrev_b32_e32 v4, 9, v1
	v_add_u32_e32 v2, -1, v4
	v_add_u32_e32 v1, 0x200, v0
	v_lshrrev_b32_e32 v3, 1, v2
	s_mul_i32 s0, s96, 0x1d1
	v_add_u32_e32 v5, 1, v3
	v_cmp_lt_u32_e32 vcc, 5, v2
	v_mov_b32_e32 v8, 0
	v_mov_b64_e32 v[2:3], v[0:1]
	s_and_saveexec_b64 s[8:9], vcc
	s_cbranch_execz .LBB0_412
	s_add_i32 s1, s0, 0x400
	s_add_i32 s12, s0, 0x800
	s_add_i32 s14, s0, 0xc00
	v_readlane_b32 s10, v248, 42
	v_and_b32_e32 v6, -4, v5
	s_mov_b32 s3, s1
	s_mov_b32 s13, s12
	s_mov_b32 s15, s14
	v_lshl_add_u32 v7, v0, 2, s10
	s_mov_b32 s16, 0
	s_mov_b64 s[10:11], 0
	v_mov_b64_e32 v[2:3], v[0:1]

; template <int MODE>
; __device__ __forceinline__ void attn_body(const Job J, char* lds) {
;     ...
;   const int tid = otid(), wid = tid >> 6, lane = tid & 63, r32 = lane & 31, hi = lane >> 5;
;   char* V_lds = lds; char* K_lds = lds + 2 * SHM_V;
;   float* wsf = (float*)(lds + 2 * SHM_V + 2 * SHM_K) + wid * 64; float* li_l = wsf; float* al_l = wsf + 32;
;   const float* tab = (const float*)(lds + 2 * SHM_V + 2 * SHM_K + NW * 256) + 64;
;   constexpr int NQR = (MODE == 2) ? 4 : 8;
;   float m_reg = -1e30f, l_reg = 0; f32x16 o[4] = {}; bf16x8 qr[NQR];
;   const bf16_t* Qw = J.Qb + (size_t)(wid * QBLK + r32) * J.ldq + hi * 8;
;   char* ql = lds + 2 * SHM_V + 2 * SHM_K + NW * 256 + (wid * 8 * 64 + lane) * 16;
; #pragma unroll
;   for (int d0 = 0; d0 < NQR; ++d0) qr[d0] = *reinterpret_cast<const bf16x8*>(Qw + d0 * 16);
;   if constexpr (MODE == 2) {
; #pragma unroll
;     for (int d0 = 4; d0 < 8; ++d0) *reinterpret_cast<bf16x8*>(ql + (d0 - 4) * 1024) = *reinterpret_cast<const bf16x8*>(Qw + d0 * 16);
;     const int tok = J.tok0 + wid * QBLK + r32; const int prow = tok >> 6, pcol = tok & 63;
; #pragma unroll
;     for (int ax = 0; ax < 2; ++ax) {
;       const float* cs = J.rope + (size_t)((ax == 0 ? prow : pcol) * 16 + hi * 8) * 2;
;       bf16x8 x1 = *reinterpret_cast<const bf16x8*>(Qw + (8 + 2 * ax) * 16), x2 = *reinterpret_cast<const bf16x8*>(Qw + (9 + 2 * ax) * 16); u32x4 w1, w2;
; #pragma unroll
;       for (int i = 0; i < 4; ++i) {
;         const f32x4 t = *(const f32x4*)(cs + 4 * i);
;         const float a0 = bf2f((bf16_t)x1[2 * i]), a1 = bf2f((bf16_t)x1[2 * i + 1]), b0 = bf2f((bf16_t)x2[2 * i]), b1 = bf2f((bf16_t)x2[2 * i + 1]);
;         w1[i] = cvt_pk_bf16(a0 * t[0] - b0 * t[1], a1 * t[2] - b1 * t[3]);
;         w2[i] = cvt_pk_bf16(a0 * t[1] + b0 * t[0], a1 * t[3] + b1 * t[2]);
; __device__ __forceinline__ void na_task(const Params& p, int task, char* shm) {
;     ...
;   att::Job J;
;   J.Qb = P + (size_t)(b * 2048 + qb * 256) * ABIN + h * 128; J.ldq = ABIN;
;   J.Kb = P + 1024 + h * 128; J.Vb = P + 2048 + h * 128; J.ldk = ABIN; J.Pe = nullptr;
;   J.Ob = MIX + (size_t)(b * 2048 + qb * 256) * DM + h * 128; J.ldo = DM;
;   const int r0 = qb * 4; const int lo = min(max(r0 - 4, 0), 24), hiw = min(max(r0 - 1, 0), 24) + 7;
;   J.lo = lo; J.nwin = hiw - lo + 1; J.qb4 = r0;
;   J.nA = 4; J.rowA = ML + b * 256; J.rowB = b * 2048 + lo * 64;
;   J.NT = (4 + J.nwin + 1) & ~1;
.LBB0_419:
	s_or_b64 exec, exec, s[4:5]
	s_ashr_i32 s0, s99, 6
	s_and_b32 s3, s99, 7
	s_lshl_b32 s1, s0, 11
	s_lshl_b32 s4, s3, 8
	s_or_b32 s94, s1, s4
	s_mul_i32 s5, s94, 0x2800
	s_mul_hi_i32 s4, s94, 0x2800
	s_add_u32 s5, s19, s5
	v_readlane_b32 s6, v248, 35
	s_addc_u32 s6, s6, s4
	s_lshl_b32 s8, s96, 8
	s_add_u32 s4, s5, s8
	s_addc_u32 s5, s6, 0
	v_readlane_b32 s6, v248, 36
	s_add_u32 s6, s6, s8
	v_readlane_b32 s7, v248, 37
	s_addc_u32 s7, s7, 0
	v_readlane_b32 s9, v248, 38
	s_add_u32 s8, s9, s8
	v_readlane_b32 s9, v248, 39
	v_mov_b32_e32 v48, v170
	s_addc_u32 s9, s9, 0
	s_lshl_b32 s10, s0, 8
	s_waitcnt lgkmcnt(0)
	s_barrier
	s_add_i32 s0, s10, 0x4000
	v_ashrrev_i32_e32 v205, 4, v48
	v_lshlrev_b32_e32 v18, 3, v48
	v_add_u32_e32 v206, 32, v205
	v_and_b32_e32 v0, 0x78, v18
	v_add_u32_e32 v8, s0, v205
	v_mov_b64_e32 v[32:33], s[8:9]
	v_add_u32_e32 v12, s0, v206
	v_lshlrev_b32_e32 v158, 1, v0
	v_mad_i64_i32 v[0:1], s[12:13], v8, s81, v[32:33]
	v_mad_i64_i32 v[2:3], s[12:13], v12, s81, v[32:33]
	v_lshl_add_u64 v[0:1], v[0:1], 0, v[158:159]
	v_lshl_add_u64 v[4:5], v[2:3], 0, v[158:159]
	v_mov_b64_e32 v[34:35], s[6:7]
	global_load_dwordx4 v[0:3], v[0:1], off
	s_nop 0
	global_load_dwordx4 v[4:7], v[4:5], off
	v_mad_i64_i32 v[8:9], s[12:13], v8, s81, v[34:35]
	v_mad_i64_i32 v[12:13], s[12:13], v12, s81, v[34:35]
	v_lshl_add_u64 v[8:9], v[8:9], 0, v[158:159]
	v_lshl_add_u64 v[12:13], v[12:13], 0, v[158:159]
	global_load_dwordx4 v[8:11], v[8:9], off
	v_ashrrev_i32_e32 v203, 1, v48
	global_load_dwordx4 v[12:15], v[12:13], off
	s_movk_i32 s11, 0xffe0
	v_bfe_u32 v161, v48, 5, 1
	v_bfi_b32 v19, s11, v203, v48
	v_mov_b64_e32 v[16:17], s[4:5]
	v_mad_i64_i32 v[16:17], s[4:5], v19, s81, v[16:17]
	v_lshlrev_b32_e32 v164, 4, v161
	v_mov_b32_e32 v165, v159
	v_lshl_add_u64 v[16:17], v[16:17], 0, v[164:165]
	global_load_dwordx4 v[116:119], v[16:17], off
	global_load_dwordx4 v[112:115], v[16:17], off offset:32
	global_load_dwordx4 v[124:127], v[16:17], off offset:64
	global_load_dwordx4 v[120:123], v[16:17], off offset:96
	global_load_dwordx4 v[108:111], v[16:17], off offset:128
	global_load_dwordx4 v[104:107], v[16:17], off offset:160
	global_load_dwordx4 v[100:103], v[16:17], off offset:192
	global_load_dwordx4 v[96:99], v[16:17], off offset:224
	v_and_b32_e32 v19, 0xfffff0, v205
	v_lshlrev_b32_e32 v20, 1, v205
	v_lshrrev_b32_e32 v21, 1, v205
	v_and_b32_e32 v22, 3, v205
	v_and_or_b32 v19, v20, 8, v19
	v_and_or_b32 v20, v21, 4, v22
	v_and_b32_e32 v21, 0xfffff0, v206
	v_lshlrev_b32_e32 v22, 1, v206
	v_bfe_u32 v18, v18, 5, 2
	v_lshrrev_b32_e32 v19, 1, v19
	v_and_or_b32 v21, v22, 8, v21
	v_or_b32_e32 v19, v19, v18
	v_lshrrev_b32_e32 v21, 1, v21
	v_lshlrev_b32_e32 v20, 6, v20
	v_and_b32_e32 v25, 48, v158
	v_lshlrev_b32_e32 v19, 9, v19
	v_or_b32_e32 v18, v21, v18
	s_movk_i32 s4, 0x70
	v_or3_b32 v19, v19, v20, v25
	v_lshlrev_b32_e32 v18, 9, v18
	v_and_b32_e32 v163, 31, v48
	v_lshlrev_b32_e32 v44, 4, v48
	v_lshl_add_u32 v23, v205, 8, 0
	v_bitop3_b32 v22, v158, v48, s4 bitop3:0x78
	v_or3_b32 v18, v18, v20, v25
	v_add_u32_e32 v208, 0, v19
	v_lshl_add_u32 v24, v206, 8, 0
	v_add_u32_e32 v207, v23, v22
	v_add_u32_e32 v209, 0, v18
	s_waitcnt vmcnt(0)
	v_lshl_add_u32 v45, v163, 8, 0
	s_waitcnt vmcnt(11)
	ds_write_b128 v208, v[0:3]
	s_waitcnt vmcnt(10)
	ds_write_b128 v209, v[4:7]
	s_waitcnt vmcnt(9)
	ds_write_b128 v207, v[8:11] offset:32768
	v_bitop3_b32 v0, v164, v44, s4 bitop3:0x78
	v_add_u32_e32 v210, v24, v22
	v_add_u32_e32 v202, v45, v0
	s_waitcnt vmcnt(8)
	ds_write_b128 v210, v[12:15] offset:32768
	s_waitcnt lgkmcnt(0)
	s_barrier
	ds_read_b128 v[0:3], v202 offset:32768
	ds_read_b128 v[4:7], v202 offset:40960
	s_waitcnt vmcnt(7) lgkmcnt(1)
	v_mfma_f32_32x32x16_bf16 v[16:31], v[0:3], v[116:119], 0
	v_and_b32_e32 v46, 0x70, v44
	v_bitop3_b32 v36, v164, v46, 32 bitop3:0x36
	v_add_u32_e32 v204, v45, v36
	ds_read_b128 v[36:39], v204 offset:32768
	ds_read_b128 v[40:43], v204 offset:40960
	s_movk_i32 s4, 0x60
	v_and_b32_e32 v188, 63, v48
	v_lshlrev_b32_e32 v49, 3, v188
	s_waitcnt lgkmcnt(2)
	v_mfma_f32_32x32x16_bf16 v[0:15], v[4:7], v[116:119], 0
	v_and_or_b32 v191, v203, 32, v163
	s_waitcnt vmcnt(6) lgkmcnt(1)
	v_mfma_f32_32x32x16_bf16 v[16:31], v[36:39], v[112:115], v[16:31]
	v_bitop3_b32 v36, v164, v46, 64 bitop3:0x36
	v_add_u32_e32 v201, v45, v36
	s_waitcnt lgkmcnt(0)
	v_mfma_f32_32x32x16_bf16 v[0:15], v[40:43], v[112:115], v[0:15]
	ds_read_b128 v[36:39], v201 offset:32768
	ds_read_b128 v[40:43], v201 offset:40960
	s_waitcnt vmcnt(5) lgkmcnt(1)
	v_mfma_f32_32x32x16_bf16 v[16:31], v[36:39], v[124:127], v[16:31]
	v_bitop3_b32 v36, v164, v46, s4 bitop3:0x36
	v_add_u32_e32 v198, v45, v36
	s_movk_i32 s4, 0x80
	s_waitcnt lgkmcnt(0)
	v_mfma_f32_32x32x16_bf16 v[0:15], v[40:43], v[124:127], v[0:15]
	ds_read_b128 v[36:39], v198 offset:32768
	ds_read_b128 v[40:43], v198 offset:40960
	s_waitcnt vmcnt(4) lgkmcnt(1)
	v_mfma_f32_32x32x16_bf16 v[16:31], v[36:39], v[120:123], v[16:31]
	v_bitop3_b32 v36, v164, v46, s4 bitop3:0x36
	v_add_u32_e32 v197, v45, v36
	s_movk_i32 s4, 0xa0
	s_waitcnt lgkmcnt(0)
	v_mfma_f32_32x32x16_bf16 v[0:15], v[40:43], v[120:123], v[0:15]
	ds_read_b128 v[36:39], v197 offset:32768
	ds_read_b128 v[40:43], v197 offset:40960
	s_waitcnt vmcnt(3) lgkmcnt(1)
	v_mfma_f32_32x32x16_bf16 v[16:31], v[36:39], v[108:111], v[16:31]
	v_bitop3_b32 v36, v164, v46, s4 bitop3:0x36
	v_add_u32_e32 v196, v45, v36
	ds_read_b128 v[36:39], v196 offset:32768
	s_lshl_b32 s4, s3, 2
	v_sub_u32_e64 v47, s4, 1 clamp
	s_max_u32 s3, s4, 4
	v_readfirstlane_b32 s5, v47
	s_waitcnt lgkmcnt(1)
; #define SWAIT() asm volatile("s_waitcnt vmcnt(0)" ::: "memory")
; __device__ __forceinline__ void partialSM(f32x16& p0, f32x16& p1, float& m_reg, float& mn, float& alpha, const float C, const float THRS) {
;   float pmax = p0[0];
; #pragma unroll
;   for (int r = 1; r < 16; ++r) pmax = fmaxf(pmax, p0[r]);
; #pragma unroll
;   for (int r = 0; r < 16; ++r) pmax = fmaxf(pmax, p1[r]);
;   { auto rr = __builtin_amdgcn_permlane32_swap(__float_as_uint(pmax), __float_as_uint(pmax), false, false);
;     pmax = fmaxf(__uint_as_float(rr[0]), __uint_as_float(rr[1])); }
;   if (__builtin_expect(__all(pmax - m_reg <= THRS), 1)) { mn = m_reg; alpha = 1.f; }
;   else { mn = fmaxf(m_reg, pmax); alpha = __builtin_amdgcn_exp2f((m_reg - mn) * C); m_reg = mn; }
;   float mnC = -mn * C;
; #pragma unroll
;   for (int r = 0; r < 16; ++r) p0[r] = fmaf(p0[r], C, mnC);
; #pragma unroll
;   for (int r = 0; r < 16; ++r) p1[r] = fmaf(p1[r], C, mnC);
; #pragma unroll
;   for (int r = 0; r < 16; ++r) p0[r] = __builtin_amdgcn_exp2f(p0[r]);
; }
; template <int MODE>
; __device__ __forceinline__ void attn_body(const Job J, char* lds) {
;     ...
;   qkt<DQK>(pA0, pA1, K_lds, qr, ql, r32, hi); MASK(pA0, pA1, 0); partialSM(pA0, pA1, m_reg, mnA, alA, C, THRS);
;   SLOAD(1);
;   SWAIT(); SWRITE(1); __syncthreads();
	v_mfma_f32_32x32x16_bf16 v[0:15], v[40:43], v[108:111], v[0:15]
	v_sub_u32_e64 v40, s4, 4 clamp
	s_min_u32 s5, s5, 24
	v_readfirstlane_b32 s33, v40
	ds_read_b128 v[40:43], v196 offset:40960
	s_sub_i32 s97, s5, s3
	s_movk_i32 s5, 0xc0
	s_add_i32 s3, s97, 11
	s_waitcnt vmcnt(2) lgkmcnt(1)
	v_mfma_f32_32x32x16_bf16 v[16:31], v[36:39], v[104:107], v[16:31]
	v_bitop3_b32 v36, v164, v46, s5 bitop3:0x36
	v_add_u32_e32 v199, v45, v36
	ds_read_b128 v[36:39], v199 offset:32768
	s_add_i32 s5, 0, 0x10000
	s_and_b32 s84, s3, -2
	s_cmp_lg_u32 0, -1
	s_waitcnt lgkmcnt(1)
	v_mfma_f32_32x32x16_bf16 v[0:15], v[40:43], v[104:107], v[0:15]
	v_and_b32_e32 v40, 0x3fffffc0, v48
	v_lshl_add_u32 v165, v40, 2, s5
	ds_read_b128 v[40:43], v199 offset:40960
	s_movk_i32 s5, 0xe0
	s_waitcnt vmcnt(1) lgkmcnt(1)
	v_mfma_f32_32x32x16_bf16 v[16:31], v[36:39], v[100:103], v[16:31]
	v_and_b32_e32 v36, 0xc0, v44
	v_lshlrev_b32_e32 v37, 1, v48
	v_bitop3_b32 v38, v164, v46, s5 bitop3:0x36
	v_and_or_b32 v36, v49, 24, v36
	v_and_b32_e32 v37, 32, v37
	v_add_u32_e32 v200, v45, v38
	v_and_b32_e32 v38, 0x100, v49
	ds_read_b128 v[44:47], v200 offset:32768
	s_waitcnt lgkmcnt(1)
	v_mfma_f32_32x32x16_bf16 v[0:15], v[40:43], v[100:103], v[0:15]
	v_or3_b32 v189, v36, v37, v38
	ds_read_b128 v[38:41], v200 offset:40960
	s_cselect_b32 s5, 0, 0
	v_ashrrev_i32_e32 v36, 7, v48
	v_add_u32_e32 v194, s5, v189
	v_add_u32_e32 v192, s4, v36
	v_max_i32_e32 v37, 4, v192
	s_waitcnt vmcnt(0) lgkmcnt(0)
	v_mfma_f32_32x32x16_bf16 v[0:15], v[38:41], v[96:99], v[0:15]
	v_add_u32_e32 v40, s10, v205
	v_add_u32_e32 v37, -4, v37
	v_min_u32_e32 v193, 24, v37
	v_sub_u32_e64 v37, v191, 8 clamp
	v_min_u32_e32 v190, 48, v37
	v_add_u32_e32 v195, 8, v193
	v_mfma_f32_32x32x16_bf16 v[16:31], v[44:47], v[96:99], v[16:31]
	v_add_u32_e32 v46, 0x4040, v40
	v_add_u32_e32 v47, 0x4060, v40
	v_mad_i64_i32 v[38:39], s[4:5], v46, s81, v[32:33]
	v_mad_i64_i32 v[32:33], s[4:5], v47, s81, v[32:33]
	v_lshl_add_u64 v[38:39], v[38:39], 0, v[158:159]
	v_lshl_add_u64 v[32:33], v[32:33], 0, v[158:159]
	global_load_dwordx4 v[38:41], v[38:39], off
	s_nop 0
	global_load_dwordx4 v[42:45], v[32:33], off
	v_mad_i64_i32 v[32:33], s[4:5], v46, s81, v[34:35]
	v_mad_i64_i32 v[34:35], s[4:5], v47, s81, v[34:35]
	v_lshl_add_u64 v[32:33], v[32:33], 0, v[158:159]
	v_lshl_add_u64 v[46:47], v[34:35], 0, v[158:159]
	global_load_dwordx4 v[32:35], v[32:33], off
	s_nop 0
	global_load_dwordx4 v[46:49], v[46:47], off
	v_max_f32_e32 v37, v17, v17
	v_max_f32_e32 v50, v16, v16
	v_max_f32_e32 v37, v50, v37
	v_max3_f32 v37, v37, v18, v19
	v_max3_f32 v37, v37, v20, v21
	v_max3_f32 v37, v37, v22, v23
	v_max3_f32 v37, v37, v24, v25
	v_max3_f32 v37, v37, v26, v27
	v_max3_f32 v37, v37, v28, v29
	v_max3_f32 v37, v37, v30, v31
	v_max3_f32 v37, v37, v0, v1
	v_max3_f32 v37, v37, v2, v3
	v_max3_f32 v37, v37, v4, v5
	v_max3_f32 v37, v37, v6, v7
	v_max3_f32 v37, v37, v8, v9
	v_max3_f32 v37, v37, v10, v11
	v_max3_f32 v37, v37, v12, v13
	v_max3_f32 v37, v37, v14, v15
	v_mov_b32_e32 v50, v37
	s_nop 1
	v_permlane32_swap_b32_e32 v37, v50
	v_max_f32_e32 v50, v50, v50
	v_max_f32_e32 v37, v37, v37
	v_max_f32_e32 v37, v37, v50
	v_add_f32_e32 v50, 0x7149f2ca, v37
	v_max_f32_e32 v37, 0xf149f2ca, v37
	v_cmp_ge_f32_e32 vcc, s88, v50
	v_sub_f32_e32 v50, 0xf149f2ca, v37
	v_mul_f32_e32 v50, 0x3e0293ee, v50
	v_exp_f32_e32 v50, v50
	s_cmp_eq_u64 vcc, exec
	s_cselect_b64 vcc, -1, 0
	v_cndmask_b32_e32 v152, v37, v187, vcc
	v_cndmask_b32_e64 v211, v50, 1.0, vcc
	v_mul_f32_e32 v50, 0xbe0293ee, v152
	v_mov_b32_e32 v37, v50
	v_fmamk_f32 v16, v16, 0x3e0293ee, v50
	v_fmamk_f32 v17, v17, 0x3e0293ee, v50
	v_fmamk_f32 v18, v18, 0x3e0293ee, v50
	v_fmamk_f32 v19, v19, 0x3e0293ee, v50
	v_fmamk_f32 v20, v20, 0x3e0293ee, v50
	v_fmamk_f32 v21, v21, 0x3e0293ee, v50
	v_fmamk_f32 v22, v22, 0x3e0293ee, v50
	v_fmamk_f32 v23, v23, 0x3e0293ee, v50
	v_fmamk_f32 v24, v24, 0x3e0293ee, v50
	v_fmamk_f32 v25, v25, 0x3e0293ee, v50
	v_fmamk_f32 v26, v26, 0x3e0293ee, v50
	v_fmamk_f32 v27, v27, 0x3e0293ee, v50
	v_fmamk_f32 v28, v28, 0x3e0293ee, v50
	v_fmamk_f32 v29, v29, 0x3e0293ee, v50
	v_fmamk_f32 v30, v30, 0x3e0293ee, v50
	v_fmac_f32_e32 v37, 0x3e0293ee, v31
	v_exp_f32_e32 v224, v16
	v_exp_f32_e32 v226, v17
	v_exp_f32_e32 v222, v18
	v_exp_f32_e32 v225, v19
	v_exp_f32_e32 v221, v20
	v_exp_f32_e32 v223, v21
	v_exp_f32_e32 v147, v22
	v_exp_f32_e32 v218, v23
	v_exp_f32_e32 v148, v24
	v_exp_f32_e32 v155, v25
	v_exp_f32_e32 v149, v26
	v_exp_f32_e32 v154, v27
	v_exp_f32_e32 v150, v28
	v_exp_f32_e32 v153, v29
	v_exp_f32_e32 v129, v30
	v_exp_f32_e32 v151, v37
	s_waitcnt vmcnt(0)
	v_pk_fma_f32 v[130:131], v[14:15], s[80:81], v[50:51] op_sel_hi:[1,0,0]
	v_pk_fma_f32 v[132:133], v[12:13], s[80:81], v[50:51] op_sel_hi:[1,0,0]
	v_pk_fma_f32 v[134:135], v[10:11], s[80:81], v[50:51] op_sel_hi:[1,0,0]
	v_pk_fma_f32 v[136:137], v[8:9], s[80:81], v[50:51] op_sel_hi:[1,0,0]
	v_pk_fma_f32 v[138:139], v[6:7], s[80:81], v[50:51] op_sel_hi:[1,0,0]
	v_pk_fma_f32 v[140:141], v[4:5], s[80:81], v[50:51] op_sel_hi:[1,0,0]
	v_pk_fma_f32 v[142:143], v[2:3], s[80:81], v[50:51] op_sel_hi:[1,0,0]
	v_pk_fma_f32 v[144:145], v[0:1], s[80:81], v[50:51] op_sel_hi:[1,0,0]
	v_mov_b32_e32 v15, 0
	s_cmp_lt_i32 s84, -3
	v_cmp_gt_u32_e64 s[4:5], 32, v188
	s_waitcnt vmcnt(3)
	ds_write_b128 v208, v[38:41] offset:16384
	s_waitcnt vmcnt(2)
	ds_write_b128 v209, v[42:45] offset:16384
	s_waitcnt vmcnt(1)
	ds_write_b128 v207, v[32:35] offset:49152
	s_waitcnt vmcnt(0)
	ds_write_b128 v210, v[46:49] offset:49152
	s_waitcnt lgkmcnt(0)
	s_barrier
; template <int MODE>
; __device__ __forceinline__ void attn_body(const Job J, char* lds) {
;     ...
;   float m_reg = -1e30f, l_reg = 0; f32x16 o[4] = {}; bf16x8 qr[NQR];
;     ...
;   const int rq = J.qb4 + (wid >> 1), qc = (wid & 1) * 32 + r32;
;   const int rs = min(max(rq - 4, 0), 24), cs_ = min(max(qc - 8, 0), 48);
;     ...
;   f32x16 pA0, pA1, pB0, pB1; float mnA, mnB, alA, alB; bf16x8 pa0, pa1, pa2, pa3; const int NT = J.NT;
	s_cbranch_scc1 .LBB0_503
	s_lshl_b32 s95, s33, 6
	v_lshl_add_u64 v[168:169], s[6:7], 0, v[158:159]
	s_and_b32 s6, s99, 7
	s_add_i32 s95, s95, s1
	s_lshl_b32 s1, s6, 2
	s_max_u32 s1, s1, 4
	v_lshlrev_b32_e32 v0, 2, v161
	s_cmp_lg_u32 0, -1
	v_or_b32_e32 v2, 32, v0
	s_mul_i32 s73, s6, 0x1f0
	s_cselect_b32 s6, 0, 0
	v_sub_u32_e32 v2, v2, v190
	v_lshl_add_u64 v[166:167], s[8:9], 0, v[158:159]
	s_addk_i32 s6, 0x4000
	v_sub_u32_e32 v3, v0, v190
	v_cmp_gt_u32_e64 s[8:9], 16, v2
	v_or_b32_e32 v2, 1, v0
	v_add_u32_e32 v213, s6, v189
	v_cmp_gt_u32_e64 s[6:7], 16, v3
	v_or_b32_e32 v3, 33, v0
	v_sub_u32_e32 v2, v2, v190
	v_cmp_gt_u32_e64 s[10:11], 16, v2
	v_sub_u32_e32 v2, v3, v190
	v_cmp_gt_u32_e64 s[12:13], 16, v2
	v_or_b32_e32 v2, 2, v0
	v_or_b32_e32 v3, 34, v0
	v_sub_u32_e32 v2, v2, v190
	v_cmp_gt_u32_e64 s[14:15], 16, v2
	v_sub_u32_e32 v2, v3, v190
	v_cmp_gt_u32_e64 s[16:17], 16, v2
	v_or_b32_e32 v2, 3, v0
	v_or_b32_e32 v3, 35, v0
	v_sub_u32_e32 v2, v2, v190
	v_writelane_b32 v248, s20, 48
	v_cmp_gt_u32_e64 s[18:19], 16, v2
	v_sub_u32_e32 v2, v3, v190
	v_writelane_b32 v248, s21, 49
	v_cmp_gt_u32_e64 s[20:21], 16, v2
	v_or_b32_e32 v2, 8, v0
	v_or_b32_e32 v3, 40, v0
	v_sub_u32_e32 v2, v2, v190
	v_cmp_gt_u32_e64 s[22:23], 16, v2
	v_sub_u32_e32 v2, v3, v190
	v_cmp_gt_u32_e64 s[24:25], 16, v2
	v_or_b32_e32 v2, 9, v0
	v_or_b32_e32 v3, 41, v0
	v_sub_u32_e32 v2, v2, v190
	v_cmp_gt_u32_e64 s[26:27], 16, v2
	v_sub_u32_e32 v2, v3, v190
	v_cmp_gt_u32_e64 s[28:29], 16, v2
	v_or_b32_e32 v2, 10, v0
	v_or_b32_e32 v3, 42, v0
	v_sub_u32_e32 v2, v2, v190
	v_cmp_gt_u32_e64 s[30:31], 16, v2
	v_sub_u32_e32 v2, v3, v190
	v_cmp_gt_u32_e64 s[34:35], 16, v2
	v_or_b32_e32 v2, 11, v0
	v_or_b32_e32 v3, 43, v0
	v_sub_u32_e32 v2, v2, v190
	v_cmp_gt_u32_e64 s[36:37], 16, v2
	v_sub_u32_e32 v2, v3, v190
	v_cmp_gt_u32_e64 s[38:39], 16, v2
	v_or_b32_e32 v2, 16, v0
	v_or_b32_e32 v3, 48, v0
	v_sub_u32_e32 v2, v2, v190
	v_cmp_gt_u32_e64 s[40:41], 16, v2
	v_sub_u32_e32 v2, v3, v190
	v_cmp_gt_u32_e64 s[42:43], 16, v2
	v_or_b32_e32 v2, 17, v0
	v_or_b32_e32 v3, 49, v0
	v_sub_u32_e32 v2, v2, v190
	v_cmp_gt_u32_e64 s[44:45], 16, v2
	v_sub_u32_e32 v2, v3, v190
	v_cmp_gt_u32_e64 s[46:47], 16, v2
	v_or_b32_e32 v2, 18, v0
	v_or_b32_e32 v3, 50, v0
	v_sub_u32_e32 v2, v2, v190
	v_cmp_gt_u32_e64 s[48:49], 16, v2
	v_sub_u32_e32 v2, v3, v190
	v_cmp_gt_u32_e64 s[50:51], 16, v2
	v_or_b32_e32 v2, 19, v0
	v_or_b32_e32 v3, 51, v0
	v_sub_u32_e32 v2, v2, v190
	v_cmp_gt_u32_e64 s[52:53], 16, v2
	v_sub_u32_e32 v2, v3, v190
	v_cmp_gt_u32_e64 s[54:55], 16, v2
	v_or_b32_e32 v2, 24, v0
	v_or_b32_e32 v3, 56, v0
	v_sub_u32_e32 v2, v2, v190
	v_cmp_gt_u32_e64 s[56:57], 16, v2
	v_sub_u32_e32 v2, v3, v190
	v_cmp_gt_u32_e64 s[58:59], 16, v2
	v_or_b32_e32 v2, 25, v0
	v_or_b32_e32 v3, 57, v0
	v_sub_u32_e32 v2, v2, v190
	v_cmp_gt_u32_e64 s[60:61], 16, v2
	v_sub_u32_e32 v2, v3, v190
	v_cmp_gt_u32_e64 s[62:63], 16, v2
	v_or_b32_e32 v2, 26, v0
	v_or_b32_e32 v3, 58, v0
	v_sub_u32_e32 v2, v2, v190
	v_cmp_gt_u32_e64 s[64:65], 16, v2
	v_sub_u32_e32 v2, v3, v190
	v_cmp_gt_u32_e64 s[66:67], 16, v2
	v_or_b32_e32 v2, 27, v0
	v_or_b32_e32 v0, 59, v0
	s_mul_i32 s72, s1, 0x7c
	v_sub_u32_e32 v0, v0, v190
	v_lshlrev_b32_e32 v1, 2, v163
	v_cmp_gt_u32_e64 s[70:71], 16, v0
	v_add_u32_e32 v0, s72, v164
	s_movk_i32 s72, 0x7c
	v_add_u32_e32 v212, v165, v1
	v_sub_u32_e32 v0, v0, v1
	v_mul_lo_u32 v1, v36, s72
	v_sub_u32_e32 v0, v0, v1
	v_lshlrev_b32_e32 v1, 2, v203
	v_and_b32_e32 v1, 0x80, v1
	v_sub_u32_e32 v0, v0, v1
	v_sub_u32_e32 v2, v2, v190
	v_subrev_u32_e32 v0, s73, v0
	s_add_i32 s72, 0, 0x1093c
	v_mov_b32_e32 v158, 0
	v_cmp_gt_u32_e64 s[68:69], 16, v2
	s_add_i32 s84, s84, 3
	v_add_u32_e32 v214, s72, v0
	s_mov_b32 s85, -2
	v_mov_b32_e32 v48, 0
	v_mov_b32_e32 v49, v158
	v_mov_b32_e32 v50, v158
	v_mov_b32_e32 v51, v158
	v_mov_b32_e32 v52, v158
	v_mov_b32_e32 v53, v158
	v_mov_b32_e32 v54, v158
	v_mov_b32_e32 v55, v158
	v_mov_b32_e32 v56, v158
	v_mov_b32_e32 v57, v158
	v_mov_b32_e32 v58, v158
	v_mov_b32_e32 v59, v158
	v_mov_b32_e32 v60, v158
	v_mov_b32_e32 v61, v158
	v_mov_b32_e32 v62, v158
	v_mov_b32_e32 v63, v158
	v_mov_b32_e32 v32, 0
	v_mov_b32_e32 v33, v158
	v_mov_b32_e32 v34, v158
	v_mov_b32_e32 v35, v158
	v_mov_b32_e32 v36, v158
	v_mov_b32_e32 v37, v158
	v_mov_b32_e32 v38, v158
	v_mov_b32_e32 v39, v158
	v_mov_b32_e32 v40, v158
	v_mov_b32_e32 v41, v158
	v_mov_b32_e32 v42, v158
	v_mov_b32_e32 v43, v158
	v_mov_b32_e32 v44, v158
	v_mov_b32_e32 v45, v158
	v_mov_b32_e32 v46, v158
	v_mov_b32_e32 v47, v158
	v_mov_b32_e32 v16, 0
	v_mov_b32_e32 v17, v158
	v_mov_b32_e32 v18, v158
	v_mov_b32_e32 v19, v158
	v_mov_b32_e32 v20, v158
	v_mov_b32_e32 v21, v158
	v_mov_b32_e32 v22, v158
	v_mov_b32_e32 v23, v158
	v_mov_b32_e32 v24, v158
	v_mov_b32_e32 v25, v158
	v_mov_b32_e32 v26, v158
	v_mov_b32_e32 v27, v158
	v_mov_b32_e32 v28, v158
	v_mov_b32_e32 v29, v158
	v_mov_b32_e32 v30, v158
	v_mov_b32_e32 v31, v158
	v_mov_b32_e32 v0, 0
	v_mov_b32_e32 v1, v158
	v_mov_b32_e32 v2, v158
	v_mov_b32_e32 v3, v158
	v_mov_b32_e32 v4, v158
	v_mov_b32_e32 v5, v158
	v_mov_b32_e32 v6, v158
	v_mov_b32_e32 v7, v158
	v_mov_b32_e32 v8, v158
	v_mov_b32_e32 v9, v158
	v_mov_b32_e32 v10, v158
	v_mov_b32_e32 v11, v158
	v_mov_b32_e32 v12, v158
	v_mov_b32_e32 v13, v158
	v_mov_b32_e32 v14, v158
	v_mov_b32_e32 v15, v158
